# attention main loop PV phase: V-fragment LDS reads pipelined through 3 register buffers with counted lgkmcnt (was read-wait-4MFMA x10 in series); on top of v25
# speedup vs baseline: 1.0189x; 1.0189x over previous
; __device__ __forceinline__ f32x4 mfma16(bf16x8 a, bf16x8 b, f32x4 c) { return __builtin_amdgcn_mfma_f32_16x16x32_bf16(a, b, c, 0, 0, 0); }
; __device__ __forceinline__ void attn_item(CParams& p, int j2, int b, int h, int q0row, int nkeys, bf16_t* smem) {
;     ...
;     for (int kt = 0; kt < nt; ++kt) {
;         lds_sync();
; #pragma unroll
;         for (int i = 0; i < 2; ++i) {
;             *(u32x4*)(sK + (srow + i * 32) * GST + skc) = rk[i];
;             *(u32x4*)(sV + (srow + i * 32) * GST + skc) = rv[i];
;         }
;         lds_sync();
;         {
;             const int t0 = (kt + 1 < nt ? kt + 1 : kt) << 6;
; #pragma unroll
;             for (int i = 0; i < 2; ++i) {
;                 rk[i] = *(const u32x4*)(Kb + (size_t)(t0 + srow + i * 32) * 128 + skc);
;                 rv[i] = *(const u32x4*)(Vb + (size_t)(srow + i * 32) * TALL + t0 + skc);
;             }
;         }
;         bf16x8 pf[2][4];
; #pragma unroll
;         for (int ih = 0; ih < 2; ++ih) {
;             f32x4 s[4][2];
; #pragma unroll
;             for (int tt = 0; tt < 4; ++tt)
; #pragma unroll
;                 for (int i = 0; i < 2; ++i) s[tt][i] = (f32x4){-mb, -mb, -mb, -mb};
; #pragma unroll
;             for (int ks = 0; ks < 2; ++ks)
; #pragma unroll
;                 for (int tt = 0; tt < 4; ++tt) {
;                     const bf16x8 kf = lds16(sK + (tt * 16 + l16) * GST + ks * 32 + quad * 8);
; #pragma unroll
;                     for (int i = 0; i < 2; ++i) s[tt][i] = mfma16(kf, qf[ih * 2 + i][ks], s[tt][i]);
;                 }
; #pragma unroll
;             for (int i = 0; i < 2; ++i) {
; #pragma unroll
;                 for (int tt = 0; tt < 4; ++tt) {
; #pragma unroll
;                     for (int r = 0; r < 4; ++r) s[tt][i][r] = __builtin_amdgcn_exp2f(s[tt][i][r]);
;                 }
; #pragma unroll
;                 for (int ksp = 0; ksp < 2; ++ksp) pf[ksp][ih * 2 + i] = pack8(s[2 * ksp][i], s[2 * ksp + 1][i]);
;             }
;         }
.LBB0_179:
	s_add_i32 s4, s9, 1
	s_waitcnt lgkmcnt(0)
	s_barrier
	s_cmpk_lt_u32 s9, 0x83
	s_cselect_b32 s5, s4, s9
	s_lshl_b32 s6, s5, 6
	v_add_u32_e32 v188, s6, v176
	s_ashr_i32 s7, s6, 31
	v_add_u32_e32 v186, 32, v188
	v_lshl_add_u64 v[190:191], s[6:7], 1, v[180:181]
	v_ashrrev_i32_e32 v189, 31, v188
	v_ashrrev_i32_e32 v187, 31, v186
	s_cmpk_lg_i32 s4, 0x84
	s_mov_b32 s9, s4
	s_waitcnt vmcnt(3)
	ds_write_b128 v164, v[222:225]
	s_waitcnt vmcnt(2)
	ds_write_b128 v164, v[226:229] offset:9216
	s_waitcnt vmcnt(1)
	ds_write_b128 v164, v[230:233] offset:4608
	s_waitcnt vmcnt(0)
	ds_write_b128 v164, v[234:237] offset:13824
	s_waitcnt lgkmcnt(0)
	s_barrier
	ds_read_b128 v[148:151], v171 offset:4608
	ds_read_b128 v[156:159], v171 offset:4672
	ds_read_b128 v[136:139], v171
	ds_read_b128 v[132:135], v171 offset:64
	s_waitcnt lgkmcnt(3)
	v_mfma_f32_16x16x32_bf16 v[160:163], v[148:151], v[4:7], v[44:47]
	ds_read_b128 v[152:155], v171 offset:6912
	ds_read_b128 v[140:143], v171 offset:2304
	ds_read_b128 v[144:147], v171 offset:2368
	s_waitcnt lgkmcnt(5)
	v_mfma_f32_16x16x32_bf16 v[234:237], v[156:159], v[8:11], v[160:163]
	s_nop 2
	ds_read_b128 v[160:163], v171 offset:6976
	s_waitcnt lgkmcnt(5)
	v_mfma_f32_16x16x32_bf16 v[116:119], v[136:139], v[4:7], v[44:47]
	s_nop 1
	v_exp_f32_e32 v234, v234
	v_exp_f32_e32 v235, v235
	v_exp_f32_e32 v236, v236
	s_waitcnt lgkmcnt(3)
	v_mfma_f32_16x16x32_bf16 v[226:229], v[152:155], v[4:7], v[44:47]
	v_exp_f32_e32 v237, v237
	v_mfma_f32_16x16x32_bf16 v[120:123], v[136:139], v[12:15], v[44:47]
	s_waitcnt lgkmcnt(2)
	v_mfma_f32_16x16x32_bf16 v[124:127], v[140:143], v[4:7], v[44:47]
	v_mfma_f32_16x16x32_bf16 v[222:225], v[148:151], v[12:15], v[44:47]
	v_mfma_f32_16x16x32_bf16 v[230:233], v[152:155], v[12:15], v[44:47]
	v_mfma_f32_16x16x32_bf16 v[116:119], v[132:135], v[8:11], v[116:119]
	s_waitcnt lgkmcnt(0)
	v_mfma_f32_16x16x32_bf16 v[226:229], v[160:163], v[8:11], v[226:229]
	v_mfma_f32_16x16x32_bf16 v[128:131], v[140:143], v[12:15], v[44:47]
	s_nop 4
	v_exp_f32_e32 v118, v118
	v_exp_f32_e32 v119, v119
	v_exp_f32_e32 v226, v226
	v_mfma_f32_16x16x32_bf16 v[120:123], v[132:135], v[24:27], v[120:123]
	v_exp_f32_e32 v227, v227
	v_exp_f32_e32 v228, v228
	v_exp_f32_e32 v229, v229
	v_mfma_f32_16x16x32_bf16 v[124:127], v[144:147], v[8:11], v[124:127]
	v_exp_f32_e32 v116, v116
	v_exp_f32_e32 v117, v117
	s_nop 1
	v_exp_f32_e32 v120, v120
	v_mfma_f32_16x16x32_bf16 v[222:225], v[156:159], v[24:27], v[222:225]
	v_exp_f32_e32 v121, v121
	s_nop 0
	v_exp_f32_e32 v175, v124
	v_exp_f32_e32 v177, v125
	v_mfma_f32_16x16x32_bf16 v[230:233], v[160:163], v[24:27], v[230:233]
	v_cvt_pk_bf16_f32 v125, v118, v119
	v_cvt_pk_bf16_f32 v118, v226, v227
	v_cvt_pk_bf16_f32 v119, v228, v229
	v_mfma_f32_16x16x32_bf16 v[128:131], v[144:147], v[24:27], v[128:131]
	v_exp_f32_e32 v122, v122
	v_exp_f32_e32 v123, v123
	v_exp_f32_e32 v222, v222
	v_exp_f32_e32 v223, v223
	v_exp_f32_e32 v224, v224
	v_exp_f32_e32 v225, v225
	v_exp_f32_e32 v226, v230
	v_exp_f32_e32 v227, v231
	v_exp_f32_e32 v228, v232
	v_exp_f32_e32 v229, v233
	v_exp_f32_e32 v221, v126
	v_cvt_pk_bf16_f32 v124, v116, v117
	v_cvt_pk_bf16_f32 v126, v175, v177
	v_cvt_pk_bf16_f32 v116, v234, v235
	v_cvt_pk_bf16_f32 v117, v236, v237
	v_exp_f32_e32 v175, v128
	v_exp_f32_e32 v177, v129
	v_cvt_pk_bf16_f32 v128, v120, v121
	v_cvt_pk_bf16_f32 v129, v122, v123
	v_cvt_pk_bf16_f32 v120, v222, v223
	v_cvt_pk_bf16_f32 v121, v224, v225
	v_cvt_pk_bf16_f32 v122, v226, v227
	v_cvt_pk_bf16_f32 v123, v228, v229
	v_mfma_f32_16x16x32_bf16 v[222:225], v[136:139], v[28:31], v[44:47]
	v_exp_f32_e32 v127, v127
	v_exp_f32_e32 v131, v131
	v_cvt_pk_bf16_f32 v127, v221, v127
	v_mfma_f32_16x16x32_bf16 v[136:139], v[136:139], v[36:39], v[44:47]
	v_exp_f32_e32 v221, v130
	v_cvt_pk_bf16_f32 v130, v175, v177
	v_cvt_pk_bf16_f32 v131, v221, v131
	v_mfma_f32_16x16x32_bf16 v[226:229], v[140:143], v[28:31], v[44:47]
	v_mfma_f32_16x16x32_bf16 v[140:143], v[140:143], v[36:39], v[44:47]
	v_mfma_f32_16x16x32_bf16 v[230:233], v[148:151], v[28:31], v[44:47]
	v_mfma_f32_16x16x32_bf16 v[148:151], v[148:151], v[36:39], v[44:47]
	v_mfma_f32_16x16x32_bf16 v[234:237], v[152:155], v[28:31], v[44:47]
	v_mfma_f32_16x16x32_bf16 v[152:155], v[152:155], v[36:39], v[44:47]
	v_mfma_f32_16x16x32_bf16 v[222:225], v[132:135], v[32:35], v[222:225]
	v_mfma_f32_16x16x32_bf16 v[136:139], v[132:135], v[40:43], v[136:139]
	v_mfma_f32_16x16x32_bf16 v[132:135], v[144:147], v[32:35], v[226:229]
	v_mfma_f32_16x16x32_bf16 v[144:147], v[144:147], v[40:43], v[140:143]
	s_nop 5
	v_exp_f32_e32 v138, v138
	v_exp_f32_e32 v134, v134
	v_exp_f32_e32 v135, v135
	v_mfma_f32_16x16x32_bf16 v[140:143], v[156:159], v[32:35], v[230:233]
	v_exp_f32_e32 v139, v139
	v_exp_f32_e32 v136, v136
	v_exp_f32_e32 v137, v137
	v_mfma_f32_16x16x32_bf16 v[148:151], v[156:159], v[40:43], v[148:151]
	v_exp_f32_e32 v132, v132
	v_exp_f32_e32 v133, v133
	v_exp_f32_e32 v147, v147
	v_mfma_f32_16x16x32_bf16 v[156:159], v[160:163], v[32:35], v[234:237]
	v_exp_f32_e32 v175, v140
	s_nop 2
	v_exp_f32_e32 v148, v148
	v_exp_f32_e32 v149, v149
	v_mfma_f32_16x16x32_bf16 v[152:155], v[160:163], v[40:43], v[152:155]
	v_exp_f32_e32 v150, v150
	v_exp_f32_e32 v156, v156
	v_exp_f32_e32 v157, v157
	v_exp_f32_e32 v151, v151
	v_exp_f32_e32 v160, v222
	s_nop 2
	v_exp_f32_e32 v154, v154
	v_exp_f32_e32 v155, v155
	v_exp_f32_e32 v222, v143
	v_cvt_pk_bf16_f32 v143, v134, v135
	v_cvt_pk_bf16_f32 v134, v156, v157
	v_exp_f32_e32 v157, v145
	v_cvt_pk_bf16_f32 v145, v138, v139
	v_cvt_pk_bf16_f32 v139, v154, v155
	v_add_u32_e32 v154, 0x2000, v173
	v_exp_f32_e32 v158, v158
	v_exp_f32_e32 v159, v159
	v_exp_f32_e32 v156, v144
; __device__ __forceinline__ f32x4 mfma16(bf16x8 a, bf16x8 b, f32x4 c) { return __builtin_amdgcn_mfma_f32_16x16x32_bf16(a, b, c, 0, 0, 0); }
; __device__ __forceinline__ void attn_item(CParams& p, int j2, int b, int h, int q0row, int nkeys, bf16_t* smem) {
;     ...
;             const int t0 = (kt + 1 < nt ? kt + 1 : kt) << 6;
; #pragma unroll
;             for (int i = 0; i < 2; ++i) {
;                 rk[i] = *(const u32x4*)(Kb + (size_t)(t0 + srow + i * 32) * 128 + skc);
;                 rv[i] = *(const u32x4*)(Vb + (size_t)(srow + i * 32) * TALL + t0 + skc);
;             }
;     ...
;                 for (int ksp = 0; ksp < 2; ++ksp) pf[ksp][ih * 2 + i] = pack8(s[2 * ksp][i], s[2 * ksp + 1][i]);
;             }
;         }
; #pragma unroll
;         for (int ksp = 0; ksp < 2; ++ksp)
; #pragma unroll
;             for (int d = 0; d < 5; ++d) {
;                 const bf16_t* vp = sV + (d * 16 + l16) * GST + ksp * 32 + quad * 4;
;                 const bf16x8 vf = lds8x2(vp, vp + 16);
; #pragma unroll
;                 for (int i = 0; i < 4; ++i) o[d][i] = mfma16(vf, pf[ksp][i], o[d][i]);
;             }
	v_cvt_pk_bf16_f32 v144, v136, v137
	v_cvt_pk_bf16_f32 v136, v148, v149
	v_cvt_pk_bf16_f32 v137, v150, v151
	ds_read2_b64 v[148:151], v154 offset0:128 offset1:132
	v_exp_f32_e32 v161, v223
	v_exp_f32_e32 v162, v224
	v_exp_f32_e32 v163, v225
	v_cvt_pk_bf16_f32 v135, v158, v159
	v_exp_f32_e32 v158, v146
	v_exp_f32_e32 v152, v152
	v_exp_f32_e32 v153, v153
	v_exp_f32_e32 v177, v141
	v_exp_f32_e32 v221, v142
	v_cvt_pk_bf16_f32 v140, v160, v161
	v_cvt_pk_bf16_f32 v141, v162, v163
	v_cvt_pk_bf16_f32 v142, v132, v133
	v_cvt_pk_bf16_f32 v146, v156, v157
	v_cvt_pk_bf16_f32 v147, v158, v147
	v_cvt_pk_bf16_f32 v138, v152, v153
	v_cvt_pk_bf16_f32 v132, v175, v177
	v_cvt_pk_bf16_f32 v133, v221, v222
	v_add_u32_e32 v152, 0x2800, v173
	v_add_u32_e32 v153, 0x3000, v173
	ds_read2_b64 v[160:163], v152 offset0:160 offset1:164
	v_add_u32_e32 v155, 0x3800, v173
	ds_read2_b64 v[156:159], v153 offset0:192 offset1:196
	v_add_u32_e32 v175, 0x4800, v173
	v_lshlrev_b64 v[222:223], 8, v[188:189]
	v_lshl_add_u64 v[222:223], v[178:179], 0, v[222:223]
	v_lshl_add_u64 v[226:227], v[190:191], 0, v[182:183]
	global_load_dwordx4 v[222:225], v[222:223], off
	v_lshlrev_b64 v[230:231], 8, v[186:187]
	global_load_dwordx4 v[226:229], v[226:227], off
	v_lshl_add_u64 v[230:231], v[178:179], 0, v[230:231]
	v_lshl_add_u64 v[234:235], v[190:191], 0, v[184:185]
	global_load_dwordx4 v[230:233], v[230:231], off
	global_load_dwordx4 v[234:237], v[234:235], off
	s_waitcnt lgkmcnt(2)
	v_mfma_f32_16x16x32_bf16 v[112:115], v[148:151], v[124:127], v[112:115]
	v_mfma_f32_16x16x32_bf16 v[108:111], v[148:151], v[128:131], v[108:111]
	v_mfma_f32_16x16x32_bf16 v[100:103], v[148:151], v[140:143], v[100:103]
	v_mfma_f32_16x16x32_bf16 v[80:83], v[148:151], v[144:147], v[80:83]
	ds_read2_b64 v[148:151], v155 offset0:224 offset1:228
	s_waitcnt lgkmcnt(2)
	v_mfma_f32_16x16x32_bf16 v[96:99], v[160:163], v[124:127], v[96:99]
	v_mfma_f32_16x16x32_bf16 v[76:79], v[160:163], v[128:131], v[76:79]
	v_mfma_f32_16x16x32_bf16 v[60:63], v[160:163], v[140:143], v[60:63]
	v_mfma_f32_16x16x32_bf16 v[20:23], v[160:163], v[144:147], v[20:23]
	ds_read2_b64 v[160:163], v175 offset1:4
	s_waitcnt lgkmcnt(2)
	v_mfma_f32_16x16x32_bf16 v[88:91], v[156:159], v[124:127], v[88:91]
	v_mfma_f32_16x16x32_bf16 v[68:71], v[156:159], v[128:131], v[68:71]
	v_mfma_f32_16x16x32_bf16 v[52:55], v[156:159], v[140:143], v[52:55]
	v_mfma_f32_16x16x32_bf16 v[0:3], v[156:159], v[144:147], v[0:3]
	ds_read2_b64 v[156:159], v154 offset0:136 offset1:140
	s_waitcnt lgkmcnt(2)
	v_mfma_f32_16x16x32_bf16 v[92:95], v[148:151], v[124:127], v[92:95]
	v_mfma_f32_16x16x32_bf16 v[72:75], v[148:151], v[128:131], v[72:75]
	v_mfma_f32_16x16x32_bf16 v[56:59], v[148:151], v[140:143], v[56:59]
	v_mfma_f32_16x16x32_bf16 v[16:19], v[148:151], v[144:147], v[16:19]
	ds_read2_b64 v[148:151], v152 offset0:168 offset1:172
	s_waitcnt lgkmcnt(2)
	v_mfma_f32_16x16x32_bf16 v[104:107], v[160:163], v[124:127], v[104:107]
	v_mfma_f32_16x16x32_bf16 v[84:87], v[160:163], v[128:131], v[84:87]
	v_mfma_f32_16x16x32_bf16 v[64:67], v[160:163], v[140:143], v[64:67]
	v_mfma_f32_16x16x32_bf16 v[48:51], v[160:163], v[144:147], v[48:51]
	ds_read2_b64 v[160:163], v153 offset0:200 offset1:204
	s_waitcnt lgkmcnt(2)
	v_mfma_f32_16x16x32_bf16 v[112:115], v[156:159], v[116:119], v[112:115]
	v_mfma_f32_16x16x32_bf16 v[108:111], v[156:159], v[120:123], v[108:111]
	v_mfma_f32_16x16x32_bf16 v[100:103], v[156:159], v[132:135], v[100:103]
	v_mfma_f32_16x16x32_bf16 v[80:83], v[156:159], v[136:139], v[80:83]
	ds_read2_b64 v[156:159], v155 offset0:232 offset1:236
	s_waitcnt lgkmcnt(2)
	v_mfma_f32_16x16x32_bf16 v[96:99], v[148:151], v[116:119], v[96:99]
	v_mfma_f32_16x16x32_bf16 v[76:79], v[148:151], v[120:123], v[76:79]
	v_mfma_f32_16x16x32_bf16 v[60:63], v[148:151], v[132:135], v[60:63]
	v_mfma_f32_16x16x32_bf16 v[20:23], v[148:151], v[136:139], v[20:23]
	ds_read2_b64 v[148:151], v175 offset0:8 offset1:12
	s_waitcnt lgkmcnt(2)
	v_mfma_f32_16x16x32_bf16 v[88:91], v[160:163], v[116:119], v[88:91]
	v_mfma_f32_16x16x32_bf16 v[68:71], v[160:163], v[120:123], v[68:71]
	v_mfma_f32_16x16x32_bf16 v[52:55], v[160:163], v[132:135], v[52:55]
	v_mfma_f32_16x16x32_bf16 v[0:3], v[160:163], v[136:139], v[0:3]
	s_waitcnt lgkmcnt(1)
	v_mfma_f32_16x16x32_bf16 v[92:95], v[156:159], v[116:119], v[92:95]
	v_mfma_f32_16x16x32_bf16 v[72:75], v[156:159], v[120:123], v[72:75]
	v_mfma_f32_16x16x32_bf16 v[56:59], v[156:159], v[132:135], v[56:59]
	v_mfma_f32_16x16x32_bf16 v[16:19], v[156:159], v[136:139], v[16:19]
	s_waitcnt lgkmcnt(0)
	v_mfma_f32_16x16x32_bf16 v[104:107], v[148:151], v[116:119], v[104:107]
	v_mfma_f32_16x16x32_bf16 v[84:87], v[148:151], v[120:123], v[84:87]
	v_mfma_f32_16x16x32_bf16 v[64:67], v[148:151], v[132:135], v[64:67]
	v_mfma_f32_16x16x32_bf16 v[48:51], v[148:151], v[136:139], v[48:51]
	s_cbranch_scc1 .LBB0_179
; __device__ __forceinline__ void attn_item(CParams& p, int j2, int b, int h, int q0row, int nkeys, bf16_t* smem) {
;     ...
;     bf16_t* as = (bf16_t*)(p.ws + WS_AS);
; #pragma unroll
;     for (int i = 0; i < 4; ++i) {
;         const float l = __shfl(o[4][i][0], l16);
;         const float inv = 1.f / l;
;         const int row = q0row + wave * 64 + i * 16 + l16;
; #pragma unroll
;         for (int d = 0; d < 4; ++d)
;             st4bf(as + frag_off(row, h * 64 + d * 16 + quad * 4, 1024), o[d][i][0] * inv, o[d][i][1] * inv, o[d][i][2] * inv, o[d][i][3] * inv);
;     }
	s_waitcnt vmcnt(0)
	v_and_or_b32 v4, v197, 64, v220
	v_lshlrev_b32_e32 v14, 2, v4
	s_nop 1
	ds_bpermute_b32 v4, v14, v104
	v_and_or_b32 v7, v169, 16, v220
	s_lshl_b32 s78, s8, 11
	v_lshlrev_b32_e32 v164, 4, v7
	s_mov_b32 s39, s0
	s_waitcnt lgkmcnt(0)
	v_div_scale_f32 v5, s[4:5], v4, v4, 1.0
	v_rcp_f32_e32 v6, v5
	s_nop 0
	v_fma_f32 v8, -v5, v6, 1.0
	v_fmac_f32_e32 v6, v8, v6
	v_div_scale_f32 v8, vcc, 1.0, v4, 1.0
	v_mul_f32_e32 v9, v8, v6
	v_fma_f32 v10, -v5, v9, v8
	v_fmac_f32_e32 v9, v10, v6
	v_fma_f32 v5, -v5, v9, v8
	v_div_fmas_f32 v5, v5, v6, v9
	v_div_fixup_f32 v6, v5, v4, 1.0
	v_ashrrev_i32_e32 v4, 4, v219
	v_ashrrev_i32_e32 v5, 31, v4
	v_lshlrev_b64 v[4:5], 15, v[4:5]
	v_lshl_add_u64 v[4:5], s[50:51], 0, v[4:5]
	v_lshl_add_u64 v[4:5], v[4:5], 0, s[78:79]
	v_lshl_add_u64 v[8:9], v[4:5], 0, v[164:165]
	v_and_b32_e32 v4, 8, v169
	v_mov_b32_e32 v5, v165
	v_pk_mul_f32 v[10:11], v[112:113], v[6:7] op_sel_hi:[1,0]
	v_pk_mul_f32 v[12:13], v[114:115], v[6:7] op_sel_hi:[1,0]
	v_lshl_add_u64 v[8:9], v[8:9], 0, v[4:5]
	v_cvt_pk_bf16_f32 v10, v10, v11
	v_cvt_pk_bf16_f32 v11, v12, v13
	global_store_dwordx2 v[8:9], v[10:11], off
	v_pk_mul_f32 v[10:11], v[96:97], v[6:7] op_sel_hi:[1,0]
	v_pk_mul_f32 v[12:13], v[98:99], v[6:7] op_sel_hi:[1,0]
	v_cvt_pk_bf16_f32 v10, v10, v11
	v_cvt_pk_bf16_f32 v11, v12, v13
	global_store_dwordx2 v[8:9], v[10:11], off offset:512
	v_pk_mul_f32 v[10:11], v[88:89], v[6:7] op_sel_hi:[1,0]
	v_pk_mul_f32 v[12:13], v[90:91], v[6:7] op_sel_hi:[1,0]
	v_cvt_pk_bf16_f32 v10, v10, v11
	v_cvt_pk_bf16_f32 v11, v12, v13
	global_store_dwordx2 v[8:9], v[10:11], off offset:1024
	v_pk_mul_f32 v[10:11], v[92:93], v[6:7] op_sel_hi:[1,0]
	v_pk_mul_f32 v[6:7], v[94:95], v[6:7] op_sel_hi:[1,0]
	v_cvt_pk_bf16_f32 v10, v10, v11
	v_cvt_pk_bf16_f32 v11, v6, v7
	ds_bpermute_b32 v6, v14, v84
	global_store_dwordx2 v[8:9], v[10:11], off offset:1536
	s_waitcnt lgkmcnt(0)
	v_div_scale_f32 v7, s[4:5], v6, v6, 1.0
	v_rcp_f32_e32 v8, v7
	s_nop 0
	v_fma_f32 v9, -v7, v8, 1.0
	v_fmac_f32_e32 v8, v9, v8
	v_div_scale_f32 v9, vcc, 1.0, v6, 1.0
	v_mul_f32_e32 v10, v9, v8
	v_fma_f32 v11, -v7, v10, v9
	v_fmac_f32_e32 v10, v11, v8
	v_fma_f32 v7, -v7, v10, v9
	v_div_fmas_f32 v7, v7, v8, v10
	v_ashrrev_i32_e32 v8, 4, v174
	v_ashrrev_i32_e32 v9, 31, v8
	v_lshlrev_b64 v[8:9], 15, v[8:9]
	v_lshl_add_u64 v[8:9], s[50:51], 0, v[8:9]
	v_div_fixup_f32 v6, v7, v6, 1.0
	v_lshl_add_u64 v[8:9], v[8:9], 0, s[78:79]
	v_lshl_add_u64 v[8:9], v[8:9], 0, v[164:165]
	v_pk_mul_f32 v[10:11], v[108:109], v[6:7] op_sel_hi:[1,0]
	v_pk_mul_f32 v[12:13], v[110:111], v[6:7] op_sel_hi:[1,0]
	v_lshl_add_u64 v[8:9], v[8:9], 0, v[4:5]
	v_cvt_pk_bf16_f32 v10, v10, v11
	v_cvt_pk_bf16_f32 v11, v12, v13
	global_store_dwordx2 v[8:9], v[10:11], off
	v_pk_mul_f32 v[10:11], v[76:77], v[6:7] op_sel_hi:[1,0]
	v_pk_mul_f32 v[12:13], v[78:79], v[6:7] op_sel_hi:[1,0]
	v_cvt_pk_bf16_f32 v10, v10, v11
	v_cvt_pk_bf16_f32 v11, v12, v13
	global_store_dwordx2 v[8:9], v[10:11], off offset:512
	v_pk_mul_f32 v[10:11], v[68:69], v[6:7] op_sel_hi:[1,0]
	v_pk_mul_f32 v[12:13], v[70:71], v[6:7] op_sel_hi:[1,0]
	v_cvt_pk_bf16_f32 v10, v10, v11
	v_cvt_pk_bf16_f32 v11, v12, v13
	global_store_dwordx2 v[8:9], v[10:11], off offset:1024
	v_pk_mul_f32 v[10:11], v[72:73], v[6:7] op_sel_hi:[1,0]
	v_pk_mul_f32 v[6:7], v[74:75], v[6:7] op_sel_hi:[1,0]
	v_cvt_pk_bf16_f32 v10, v10, v11
	v_cvt_pk_bf16_f32 v11, v6, v7
	ds_bpermute_b32 v6, v14, v64
	global_store_dwordx2 v[8:9], v[10:11], off offset:1536
	s_waitcnt lgkmcnt(0)
	v_div_scale_f32 v7, s[4:5], v6, v6, 1.0
	v_rcp_f32_e32 v8, v7
	s_nop 0
	v_fma_f32 v9, -v7, v8, 1.0
	v_fmac_f32_e32 v8, v9, v8
	v_div_scale_f32 v9, vcc, 1.0, v6, 1.0
	v_mul_f32_e32 v10, v9, v8
	v_fma_f32 v11, -v7, v10, v9
	v_fmac_f32_e32 v10, v11, v8
	v_fma_f32 v7, -v7, v10, v9
	v_div_fmas_f32 v7, v7, v8, v10
	v_ashrrev_i32_e32 v8, 4, v172
	v_ashrrev_i32_e32 v9, 31, v8
	v_lshlrev_b64 v[8:9], 15, v[8:9]
	v_lshl_add_u64 v[8:9], s[50:51], 0, v[8:9]
	v_div_fixup_f32 v6, v7, v6, 1.0
	v_lshl_add_u64 v[8:9], v[8:9], 0, s[78:79]
	v_lshl_add_u64 v[8:9], v[8:9], 0, v[164:165]
	v_pk_mul_f32 v[10:11], v[100:101], v[6:7] op_sel_hi:[1,0]
	v_pk_mul_f32 v[12:13], v[102:103], v[6:7] op_sel_hi:[1,0]
	v_lshl_add_u64 v[8:9], v[8:9], 0, v[4:5]
	v_cvt_pk_bf16_f32 v10, v10, v11
	v_cvt_pk_bf16_f32 v11, v12, v13
	global_store_dwordx2 v[8:9], v[10:11], off
	v_pk_mul_f32 v[10:11], v[60:61], v[6:7] op_sel_hi:[1,0]
	v_pk_mul_f32 v[12:13], v[62:63], v[6:7] op_sel_hi:[1,0]
	v_cvt_pk_bf16_f32 v10, v10, v11
	v_cvt_pk_bf16_f32 v11, v12, v13
	global_store_dwordx2 v[8:9], v[10:11], off offset:512
	v_pk_mul_f32 v[10:11], v[52:53], v[6:7] op_sel_hi:[1,0]
	v_pk_mul_f32 v[12:13], v[54:55], v[6:7] op_sel_hi:[1,0]
	v_cvt_pk_bf16_f32 v10, v10, v11
	v_cvt_pk_bf16_f32 v11, v12, v13
	global_store_dwordx2 v[8:9], v[10:11], off offset:1024
	v_pk_mul_f32 v[10:11], v[56:57], v[6:7] op_sel_hi:[1,0]
	v_pk_mul_f32 v[6:7], v[58:59], v[6:7] op_sel_hi:[1,0]
	v_cvt_pk_bf16_f32 v10, v10, v11
	v_cvt_pk_bf16_f32 v11, v6, v7
	ds_bpermute_b32 v6, v14, v48
	global_store_dwordx2 v[8:9], v[10:11], off offset:1536
	s_waitcnt lgkmcnt(0)
	v_div_scale_f32 v7, s[4:5], v6, v6, 1.0
	v_rcp_f32_e32 v8, v7
	s_nop 0
	v_fma_f32 v9, -v7, v8, 1.0
	v_fmac_f32_e32 v8, v9, v8
	v_div_scale_f32 v9, vcc, 1.0, v6, 1.0
	v_mul_f32_e32 v10, v9, v8
	v_fma_f32 v11, -v7, v10, v9
	v_fmac_f32_e32 v10, v11, v8
	v_fma_f32 v7, -v7, v10, v9
	v_div_fmas_f32 v7, v7, v8, v10
	v_ashrrev_i32_e32 v8, 4, v170
	v_ashrrev_i32_e32 v9, 31, v8
	v_lshlrev_b64 v[8:9], 15, v[8:9]
	v_lshl_add_u64 v[8:9], s[50:51], 0, v[8:9]
	v_lshl_add_u64 v[8:9], v[8:9], 0, s[78:79]
	v_div_fixup_f32 v6, v7, v6, 1.0
	v_lshl_add_u64 v[8:9], v[8:9], 0, v[164:165]
	v_lshl_add_u64 v[4:5], v[8:9], 0, v[4:5]
	v_pk_mul_f32 v[8:9], v[80:81], v[6:7] op_sel_hi:[1,0]
	v_pk_mul_f32 v[10:11], v[82:83], v[6:7] op_sel_hi:[1,0]
	v_pk_mul_f32 v[0:1], v[0:1], v[6:7] op_sel_hi:[1,0]
	v_pk_mul_f32 v[2:3], v[2:3], v[6:7] op_sel_hi:[1,0]
	v_cvt_pk_bf16_f32 v8, v8, v9
	v_cvt_pk_bf16_f32 v9, v10, v11
	v_cvt_pk_bf16_f32 v0, v0, v1
	v_cvt_pk_bf16_f32 v1, v2, v3
	global_store_dwordx2 v[4:5], v[8:9], off
	v_pk_mul_f32 v[8:9], v[20:21], v[6:7] op_sel_hi:[1,0]
	v_pk_mul_f32 v[10:11], v[22:23], v[6:7] op_sel_hi:[1,0]
	global_store_dwordx2 v[4:5], v[0:1], off offset:1024
	v_pk_mul_f32 v[0:1], v[16:17], v[6:7] op_sel_hi:[1,0]
	v_pk_mul_f32 v[2:3], v[18:19], v[6:7] op_sel_hi:[1,0]
	v_cvt_pk_bf16_f32 v8, v8, v9
	v_cvt_pk_bf16_f32 v9, v10, v11
	v_cvt_pk_bf16_f32 v0, v0, v1
	v_cvt_pk_bf16_f32 v1, v2, v3
	global_store_dwordx2 v[4:5], v[8:9], off offset:512
	global_store_dwordx2 v[4:5], v[0:1], off offset:1536
	s_branch .LBB0_166
